# prologue de-serialisation in prep phase: prep_wc K/W tile loads and w_in gain-transpose loads issued together instead of dependent load-wait-write chains; chunk 1 prefetched over chunk 0 compute
# speedup vs baseline: 1.0145x; 1.0082x over previous
; __device__ void prep_wc(const Params& p, int l, int item, char* smem) {
;     ...
;     for (int ch = 0; ch < 2; ++ch) {
; #pragma unroll 4
;         for (int i = 0; i < 16; ++i) {
;             const int rl = r0 + 4 * i;
;             sK[rl * 65 + cl] = Kp[(size_t)(jt * 64 + rl) * 128 + ch * 64 + cl];
;             sW[rl * 65 + cl] = Wq[(size_t)(dt * 64 + rl) * 2048 + ch * 64 + cl];
;         }
.LBB0_541:
	s_waitcnt lgkmcnt(0)
	v_add_u32_e32 v112, s1, v2
	v_add_u32_e32 v110, s13, v2
	v_mov_b32_e32 v111, 0
	v_lshlrev_b64 v[36:37], 9, v[112:113]
	v_lshlrev_b64 v[38:39], 13, v[110:111]
	v_lshl_add_u64 v[36:37], v[16:17], 0, v[36:37]
	v_lshl_add_u64 v[38:39], v[18:19], 0, v[38:39]
	s_mov_b64 s[18:19], 0x1000
	global_load_dword v76, v[36:37], off
	global_load_dword v77, v[36:37], off offset:2048
	v_lshl_add_u64 v[36:37], v[36:37], 0, s[18:19]
	global_load_dword v78, v[36:37], off
	global_load_dword v79, v[36:37], off offset:2048
	v_lshl_add_u64 v[36:37], v[36:37], 0, s[18:19]
	global_load_dword v80, v[36:37], off
	global_load_dword v81, v[36:37], off offset:2048
	v_lshl_add_u64 v[36:37], v[36:37], 0, s[18:19]
	global_load_dword v82, v[36:37], off
	global_load_dword v83, v[36:37], off offset:2048
	v_lshl_add_u64 v[36:37], v[36:37], 0, s[18:19]
	global_load_dword v84, v[36:37], off
	global_load_dword v85, v[36:37], off offset:2048
	v_lshl_add_u64 v[36:37], v[36:37], 0, s[18:19]
	global_load_dword v86, v[36:37], off
	global_load_dword v87, v[36:37], off offset:2048
	v_lshl_add_u64 v[36:37], v[36:37], 0, s[18:19]
	global_load_dword v88, v[36:37], off
	global_load_dword v89, v[36:37], off offset:2048
	v_lshl_add_u64 v[36:37], v[36:37], 0, s[18:19]
	global_load_dword v90, v[36:37], off
	global_load_dword v91, v[36:37], off offset:2048
	global_load_dword v92, v[38:39], off
	v_lshl_add_u64 v[38:39], s[18:19], 3, v[38:39]
	global_load_dword v93, v[38:39], off
	v_lshl_add_u64 v[38:39], s[18:19], 3, v[38:39]
	global_load_dword v94, v[38:39], off
	v_lshl_add_u64 v[38:39], s[18:19], 3, v[38:39]
	global_load_dword v95, v[38:39], off
	v_lshl_add_u64 v[38:39], s[18:19], 3, v[38:39]
	global_load_dword v96, v[38:39], off
	v_lshl_add_u64 v[38:39], s[18:19], 3, v[38:39]
	global_load_dword v97, v[38:39], off
	v_lshl_add_u64 v[38:39], s[18:19], 3, v[38:39]
	global_load_dword v98, v[38:39], off
	v_lshl_add_u64 v[38:39], s[18:19], 3, v[38:39]
	global_load_dword v99, v[38:39], off
	v_lshl_add_u64 v[38:39], s[18:19], 3, v[38:39]
	global_load_dword v100, v[38:39], off
	v_lshl_add_u64 v[38:39], s[18:19], 3, v[38:39]
	global_load_dword v101, v[38:39], off
	v_lshl_add_u64 v[38:39], s[18:19], 3, v[38:39]
	global_load_dword v102, v[38:39], off
	v_lshl_add_u64 v[38:39], s[18:19], 3, v[38:39]
	global_load_dword v103, v[38:39], off
	v_lshl_add_u64 v[38:39], s[18:19], 3, v[38:39]
	global_load_dword v104, v[38:39], off
	v_lshl_add_u64 v[38:39], s[18:19], 3, v[38:39]
	global_load_dword v105, v[38:39], off
	v_lshl_add_u64 v[38:39], s[18:19], 3, v[38:39]
	global_load_dword v106, v[38:39], off
	v_lshl_add_u64 v[38:39], s[18:19], 3, v[38:39]
	global_load_dword v107, v[38:39], off
	v_lshl_add_u32 v40, v2, 6, v2
	v_add_lshl_u32 v40, v40, v0, 2
	s_waitcnt vmcnt(31)
	ds_write_b32 v40, v76
	s_waitcnt vmcnt(30)
	ds_write_b32 v40, v77 offset:1040
	s_waitcnt vmcnt(29)
	ds_write_b32 v40, v78 offset:2080
	s_waitcnt vmcnt(28)
	ds_write_b32 v40, v79 offset:3120
	s_waitcnt vmcnt(27)
	ds_write_b32 v40, v80 offset:4160
	s_waitcnt vmcnt(26)
	ds_write_b32 v40, v81 offset:5200
	s_waitcnt vmcnt(25)
	ds_write_b32 v40, v82 offset:6240
	s_waitcnt vmcnt(24)
	ds_write_b32 v40, v83 offset:7280
	s_waitcnt vmcnt(23)
	ds_write_b32 v40, v84 offset:8320
	s_waitcnt vmcnt(22)
	ds_write_b32 v40, v85 offset:9360
	s_waitcnt vmcnt(21)
	ds_write_b32 v40, v86 offset:10400
	s_waitcnt vmcnt(20)
	ds_write_b32 v40, v87 offset:11440
	s_waitcnt vmcnt(19)
	ds_write_b32 v40, v88 offset:12480
	s_waitcnt vmcnt(18)
	ds_write_b32 v40, v89 offset:13520
	s_waitcnt vmcnt(17)
	ds_write_b32 v40, v90 offset:14560
	s_waitcnt vmcnt(16)
	ds_write_b32 v40, v91 offset:15600
	s_waitcnt vmcnt(15)
	ds_write_b32 v40, v92 offset:16640
	s_waitcnt vmcnt(14)
	ds_write_b32 v40, v93 offset:17680
	s_waitcnt vmcnt(13)
	ds_write_b32 v40, v94 offset:18720
	s_waitcnt vmcnt(12)
	ds_write_b32 v40, v95 offset:19760
	s_waitcnt vmcnt(11)
	ds_write_b32 v40, v96 offset:20800
	s_waitcnt vmcnt(10)
	ds_write_b32 v40, v97 offset:21840
	s_waitcnt vmcnt(9)
	ds_write_b32 v40, v98 offset:22880
	s_waitcnt vmcnt(8)
; __device__ void prep_wc(const Params& p, int l, int item, char* smem) {
;     ...
;     float acc[4][4];
; #pragma unroll
;     for (int a = 0; a < 4; ++a)
; #pragma unroll
;         for (int b = 0; b < 4; ++b) acc[a][b] = 0.f;
;     for (int ch = 0; ch < 2; ++ch) {
; #pragma unroll 4
;         for (int i = 0; i < 16; ++i) {
;             const int rl = r0 + 4 * i;
;             sK[rl * 65 + cl] = Kp[(size_t)(jt * 64 + rl) * 128 + ch * 64 + cl];
;             sW[rl * 65 + cl] = Wq[(size_t)(dt * 64 + rl) * 2048 + ch * 64 + cl];
;         }
;         __syncthreads();
	ds_write_b32 v40, v99 offset:23920
	s_waitcnt vmcnt(7)
	ds_write_b32 v40, v100 offset:24960
	s_waitcnt vmcnt(6)
	ds_write_b32 v40, v101 offset:26000
	s_waitcnt vmcnt(5)
	ds_write_b32 v40, v102 offset:27040
	s_waitcnt vmcnt(4)
	ds_write_b32 v40, v103 offset:28080
	s_waitcnt vmcnt(3)
	ds_write_b32 v40, v104 offset:29120
	s_waitcnt vmcnt(2)
	ds_write_b32 v40, v105 offset:30160
	s_waitcnt vmcnt(1)
	ds_write_b32 v40, v106 offset:31200
	s_waitcnt vmcnt(0)
	ds_write_b32 v40, v107 offset:32240
	v_add_u32_e32 v112, s1, v2
	v_add_u32_e32 v110, s13, v2
	v_mov_b32_e32 v111, 0
	v_lshlrev_b64 v[36:37], 9, v[112:113]
	v_lshlrev_b64 v[38:39], 13, v[110:111]
	v_lshl_add_u64 v[36:37], v[16:17], 0, v[36:37]
	v_lshl_add_u64 v[38:39], v[18:19], 0, v[38:39]
	s_mov_b64 s[18:19], 0x1000
	global_load_dword v76, v[36:37], off offset:256
	global_load_dword v77, v[36:37], off offset:2304
	v_lshl_add_u64 v[36:37], v[36:37], 0, s[18:19]
	global_load_dword v78, v[36:37], off offset:256
	global_load_dword v79, v[36:37], off offset:2304
	v_lshl_add_u64 v[36:37], v[36:37], 0, s[18:19]
	global_load_dword v80, v[36:37], off offset:256
	global_load_dword v81, v[36:37], off offset:2304
	v_lshl_add_u64 v[36:37], v[36:37], 0, s[18:19]
	global_load_dword v82, v[36:37], off offset:256
	global_load_dword v83, v[36:37], off offset:2304
	v_lshl_add_u64 v[36:37], v[36:37], 0, s[18:19]
	global_load_dword v84, v[36:37], off offset:256
	global_load_dword v85, v[36:37], off offset:2304
	v_lshl_add_u64 v[36:37], v[36:37], 0, s[18:19]
	global_load_dword v86, v[36:37], off offset:256
	global_load_dword v87, v[36:37], off offset:2304
	v_lshl_add_u64 v[36:37], v[36:37], 0, s[18:19]
	global_load_dword v88, v[36:37], off offset:256
	global_load_dword v89, v[36:37], off offset:2304
	v_lshl_add_u64 v[36:37], v[36:37], 0, s[18:19]
	global_load_dword v90, v[36:37], off offset:256
	global_load_dword v91, v[36:37], off offset:2304
	global_load_dword v92, v[38:39], off offset:256
	v_lshl_add_u64 v[38:39], s[18:19], 3, v[38:39]
	global_load_dword v93, v[38:39], off offset:256
	v_lshl_add_u64 v[38:39], s[18:19], 3, v[38:39]
	global_load_dword v94, v[38:39], off offset:256
	v_lshl_add_u64 v[38:39], s[18:19], 3, v[38:39]
	global_load_dword v95, v[38:39], off offset:256
	v_lshl_add_u64 v[38:39], s[18:19], 3, v[38:39]
	global_load_dword v96, v[38:39], off offset:256
	v_lshl_add_u64 v[38:39], s[18:19], 3, v[38:39]
	global_load_dword v97, v[38:39], off offset:256
	v_lshl_add_u64 v[38:39], s[18:19], 3, v[38:39]
	global_load_dword v98, v[38:39], off offset:256
	v_lshl_add_u64 v[38:39], s[18:19], 3, v[38:39]
	global_load_dword v99, v[38:39], off offset:256
	v_lshl_add_u64 v[38:39], s[18:19], 3, v[38:39]
	global_load_dword v100, v[38:39], off offset:256
	v_lshl_add_u64 v[38:39], s[18:19], 3, v[38:39]
	global_load_dword v101, v[38:39], off offset:256
	v_lshl_add_u64 v[38:39], s[18:19], 3, v[38:39]
	global_load_dword v102, v[38:39], off offset:256
	v_lshl_add_u64 v[38:39], s[18:19], 3, v[38:39]
	global_load_dword v103, v[38:39], off offset:256
	v_lshl_add_u64 v[38:39], s[18:19], 3, v[38:39]
	global_load_dword v104, v[38:39], off offset:256
	v_lshl_add_u64 v[38:39], s[18:19], 3, v[38:39]
	global_load_dword v105, v[38:39], off offset:256
	v_lshl_add_u64 v[38:39], s[18:19], 3, v[38:39]
	global_load_dword v106, v[38:39], off offset:256
	v_lshl_add_u64 v[38:39], s[18:19], 3, v[38:39]
	global_load_dword v107, v[38:39], off offset:256
	v_lshlrev_b32_e32 v112, 2, v0
	v_ashrrev_i32_e32 v5, 2, v4
	v_lshlrev_b32_e32 v4, 2, v4
	v_and_b32_e32 v30, 60, v4
	v_or_b32_e32 v4, 3, v5
	v_mul_lo_u32 v33, v4, s6
	v_mov_b32_e32 v4, 0x4100
	v_and_b32_e32 v31, -4, v5
	v_mad_u32_u24 v34, v30, s6, v4
	v_mov_b32_e32 v4, 0
	v_mul_lo_u32 v32, v31, s6
	s_mov_b32 s16, 0
	v_mov_b32_e32 v5, v4
	v_mov_b32_e32 v6, v4
	v_mov_b32_e32 v7, v4
	v_mov_b32_e32 v8, v4
	v_mov_b32_e32 v9, v4
	v_mov_b32_e32 v10, v4
	v_mov_b32_e32 v11, v4
	v_mov_b32_e32 v12, v4
	v_mov_b32_e32 v13, v4
	v_mov_b32_e32 v14, v4
	v_mov_b32_e32 v15, v4
	v_mov_b32_e32 v26, v4
	v_mov_b32_e32 v27, v4
	v_mov_b32_e32 v28, v4
	v_mov_b32_e32 v29, v4
	s_waitcnt lgkmcnt(0)
	s_barrier

; __device__ void prep_wc(const Params& p, int l, int item, char* smem) {
;     ...
;         for (int i = 0; i < 16; ++i) {
;             const int rl = r0 + 4 * i;
;             sK[rl * 65 + cl] = Kp[(size_t)(jt * 64 + rl) * 128 + ch * 64 + cl];
;             sW[rl * 65 + cl] = Wq[(size_t)(dt * 64 + rl) * 2048 + ch * 64 + cl];
;         }
;         __syncthreads();
.LBB0_545:
	v_lshl_add_u32 v40, v2, 6, v2
	v_add_lshl_u32 v40, v40, v0, 2
	s_waitcnt vmcnt(31)
	ds_write_b32 v40, v76
	s_waitcnt vmcnt(30)
	ds_write_b32 v40, v77 offset:1040
	s_waitcnt vmcnt(29)
	ds_write_b32 v40, v78 offset:2080
	s_waitcnt vmcnt(28)
	ds_write_b32 v40, v79 offset:3120
	s_waitcnt vmcnt(27)
	ds_write_b32 v40, v80 offset:4160
	s_waitcnt vmcnt(26)
	ds_write_b32 v40, v81 offset:5200
	s_waitcnt vmcnt(25)
	ds_write_b32 v40, v82 offset:6240
	s_waitcnt vmcnt(24)
	ds_write_b32 v40, v83 offset:7280
	s_waitcnt vmcnt(23)
	ds_write_b32 v40, v84 offset:8320
	s_waitcnt vmcnt(22)
	ds_write_b32 v40, v85 offset:9360
	s_waitcnt vmcnt(21)
	ds_write_b32 v40, v86 offset:10400
	s_waitcnt vmcnt(20)
	ds_write_b32 v40, v87 offset:11440
	s_waitcnt vmcnt(19)
	ds_write_b32 v40, v88 offset:12480
	s_waitcnt vmcnt(18)
	ds_write_b32 v40, v89 offset:13520
	s_waitcnt vmcnt(17)
	ds_write_b32 v40, v90 offset:14560
	s_waitcnt vmcnt(16)
	ds_write_b32 v40, v91 offset:15600
	s_waitcnt vmcnt(15)
	ds_write_b32 v40, v92 offset:16640
	s_waitcnt vmcnt(14)
	ds_write_b32 v40, v93 offset:17680
	s_waitcnt vmcnt(13)
	ds_write_b32 v40, v94 offset:18720
	s_waitcnt vmcnt(12)
	ds_write_b32 v40, v95 offset:19760
	s_waitcnt vmcnt(11)
	ds_write_b32 v40, v96 offset:20800
	s_waitcnt vmcnt(10)
	ds_write_b32 v40, v97 offset:21840
	s_waitcnt vmcnt(9)
	ds_write_b32 v40, v98 offset:22880
	s_waitcnt vmcnt(8)
	ds_write_b32 v40, v99 offset:23920
	s_waitcnt vmcnt(7)
	ds_write_b32 v40, v100 offset:24960
	s_waitcnt vmcnt(6)
	ds_write_b32 v40, v101 offset:26000
	s_waitcnt vmcnt(5)
	ds_write_b32 v40, v102 offset:27040
	s_waitcnt vmcnt(4)
	ds_write_b32 v40, v103 offset:28080
	s_waitcnt vmcnt(3)
	ds_write_b32 v40, v104 offset:29120
	s_waitcnt vmcnt(2)
	ds_write_b32 v40, v105 offset:30160
	s_waitcnt vmcnt(1)
	ds_write_b32 v40, v106 offset:31200
	s_waitcnt vmcnt(0)
	ds_write_b32 v40, v107 offset:32240
	s_mov_b32 s14, 0
	s_waitcnt lgkmcnt(0)
	s_barrier

; __device__ void prep_transpose(const float* src, int ldn, int nvalid, const float* g, bf16_t* dst, int kt, int nt, char* smem) {
;     ...
;     for (int i = 0; i < 16; ++i) {
;         const int row = r0 + 4 * i, k = kt * 64 + row, n = nt * 64 + col;
;         float v = 0.f;
;         if (n < nvalid) { v = src[(size_t)k * ldn + n]; if (g) v *= g[k]; }
;         sm[row * 65 + col] = v;
;     }
.LBB0_559:
	v_mov_b32_e32 v76, 0
	v_mov_b32_e32 v77, 0
	v_mov_b32_e32 v78, 0
	v_mov_b32_e32 v79, 0
	v_mov_b32_e32 v80, 0
	v_mov_b32_e32 v81, 0
	v_mov_b32_e32 v82, 0
	v_mov_b32_e32 v83, 0
	v_mov_b32_e32 v84, 0
	v_mov_b32_e32 v85, 0
	v_mov_b32_e32 v86, 0
	v_mov_b32_e32 v87, 0
	v_mov_b32_e32 v88, 0
	v_mov_b32_e32 v89, 0
	v_mov_b32_e32 v90, 0
	v_mov_b32_e32 v91, 0
	v_mov_b32_e32 v92, v115
	v_mov_b32_e32 v93, v115
	v_mov_b32_e32 v94, v115
	v_mov_b32_e32 v95, v115
	v_mov_b32_e32 v96, v115
	v_mov_b32_e32 v97, v115
	v_mov_b32_e32 v98, v115
	v_mov_b32_e32 v99, v115
	v_mov_b32_e32 v100, v115
	v_mov_b32_e32 v101, v115
	v_mov_b32_e32 v102, v115
	v_mov_b32_e32 v103, v115
	v_mov_b32_e32 v104, v115
	v_mov_b32_e32 v105, v115
	v_mov_b32_e32 v106, v115
	v_mov_b32_e32 v107, v115
	s_and_saveexec_b64 s[24:25], s[38:39]
	s_cbranch_execz .Lwin_ld_done
	v_lshl_add_u64 v[18:19], v[12:13], 0, s[34:35]
	global_load_dword v76, v[18:19], off
	v_lshl_add_u64 v[20:21], v[8:9], 0, s[34:35]
	global_load_dword v77, v[20:21], off
	v_lshl_add_u64 v[108:109], v[6:7], 0, s[34:35]
	global_load_dword v78, v[108:109], off
	v_lshl_add_u64 v[110:111], v[2:3], 0, s[34:35]
	global_load_dword v79, v[110:111], off
	s_add_u32 s34, s34, 0x28200
	s_addc_u32 s35, s35, 0
	v_lshl_add_u64 v[18:19], v[12:13], 0, s[34:35]
	global_load_dword v80, v[18:19], off
	v_lshl_add_u64 v[20:21], v[8:9], 0, s[34:35]
	global_load_dword v81, v[20:21], off
	v_lshl_add_u64 v[108:109], v[6:7], 0, s[34:35]
	global_load_dword v82, v[108:109], off
	v_lshl_add_u64 v[110:111], v[2:3], 0, s[34:35]
	global_load_dword v83, v[110:111], off
	s_add_u32 s34, s34, 0x28200
	s_addc_u32 s35, s35, 0
	v_lshl_add_u64 v[18:19], v[12:13], 0, s[34:35]
	global_load_dword v84, v[18:19], off
	v_lshl_add_u64 v[20:21], v[8:9], 0, s[34:35]
	global_load_dword v85, v[20:21], off
	v_lshl_add_u64 v[108:109], v[6:7], 0, s[34:35]
	global_load_dword v86, v[108:109], off
	v_lshl_add_u64 v[110:111], v[2:3], 0, s[34:35]
	global_load_dword v87, v[110:111], off
	s_add_u32 s34, s34, 0x28200
	s_addc_u32 s35, s35, 0
	v_lshl_add_u64 v[18:19], v[12:13], 0, s[34:35]
	global_load_dword v88, v[18:19], off
	v_lshl_add_u64 v[20:21], v[8:9], 0, s[34:35]
	global_load_dword v89, v[20:21], off
	v_lshl_add_u64 v[108:109], v[6:7], 0, s[34:35]
	global_load_dword v90, v[108:109], off
	v_lshl_add_u64 v[110:111], v[2:3], 0, s[34:35]
	global_load_dword v91, v[110:111], off
	s_add_u32 s34, s34, 0x28200
	s_addc_u32 s35, s35, 0
	s_andn2_b64 vcc, exec, s[26:27]
	s_cbranch_vccnz .Lwin_ld_done
	v_lshl_add_u64 v[18:19], v[4:5], 0, s[22:23]
	global_load_dword v92, v[18:19], off
	global_load_dword v93, v[18:19], off offset:16
	global_load_dword v94, v[18:19], off offset:32
	global_load_dword v95, v[18:19], off offset:48
	global_load_dword v96, v[18:19], off offset:64
	global_load_dword v97, v[18:19], off offset:80
	global_load_dword v98, v[18:19], off offset:96
	global_load_dword v99, v[18:19], off offset:112
	global_load_dword v100, v[18:19], off offset:128
	global_load_dword v101, v[18:19], off offset:144
	global_load_dword v102, v[18:19], off offset:160
	global_load_dword v103, v[18:19], off offset:176
	global_load_dword v104, v[18:19], off offset:192
	global_load_dword v105, v[18:19], off offset:208
	global_load_dword v106, v[18:19], off offset:224
	global_load_dword v107, v[18:19], off offset:240
.Lwin_ld_done:
	s_or_b64 exec, exec, s[24:25]
	s_waitcnt vmcnt(0)
	v_pk_mul_f32 v[76:77], v[76:77], v[92:93]
	v_pk_mul_f32 v[78:79], v[78:79], v[94:95]
	v_pk_mul_f32 v[80:81], v[80:81], v[96:97]
	v_pk_mul_f32 v[82:83], v[82:83], v[98:99]
	v_pk_mul_f32 v[84:85], v[84:85], v[100:101]
	v_pk_mul_f32 v[86:87], v[86:87], v[102:103]
	v_pk_mul_f32 v[88:89], v[88:89], v[104:105]
	v_pk_mul_f32 v[90:91], v[90:91], v[106:107]
	ds_write_b32 v15, v76
	ds_write_b32 v15, v77 offset:1040
	ds_write_b32 v15, v78 offset:2080
	ds_write_b32 v15, v79 offset:3120
	ds_write_b32 v15, v80 offset:4160
	ds_write_b32 v15, v81 offset:5200
	ds_write_b32 v15, v82 offset:6240
	ds_write_b32 v15, v83 offset:7280
	ds_write_b32 v15, v84 offset:8320
	ds_write_b32 v15, v85 offset:9360
	ds_write_b32 v15, v86 offset:10400
	ds_write_b32 v15, v87 offset:11440
	ds_write_b32 v15, v88 offset:12480
	ds_write_b32 v15, v89 offset:13520
	ds_write_b32 v15, v90 offset:14560
	ds_write_b32 v15, v91 offset:15600
